# k20
# baseline (speedup 1.0000x reference)
.LBB0_1336:
	s_andn2_b64 vcc, exec, s[62:63]
	s_cbranch_vccnz .Lpa_early_done
	s_mul_i32 s12, s23, 0x6c00
	v_add_u32_e32 v7, s12, v167
	ds_read_b128 v[168:171], v7 offset:9216
	ds_read_b128 v[8:11], v7 offset:9248
	ds_read_b128 v[12:15], v7 offset:9280
	ds_read_b128 v[112:115], v7 offset:9312
	ds_read_b128 v[116:119], v7 offset:13824
	ds_read_b128 v[120:123], v7 offset:13856
	ds_read_b128 v[124:127], v7 offset:13888
	ds_read_b128 v[172:175], v7 offset:13920

.LBB0_1338:
	s_setprio 1
	s_andn2_b64 vcc, exec, s[62:63]
	s_cbranch_vccnz .LBB0_1340
	s_mul_i32 s12, s23, 0x6c00
	v_add_u32_e32 v3, s12, v167
	s_waitcnt lgkmcnt(7)
	v_mfma_f32_32x32x16_bf16 v[16:31], v[168:171], v[100:103], v[16:31]
	ds_read_b128 v[168:171], v3 offset:18432
	s_waitcnt lgkmcnt(7)
	v_mfma_f32_32x32x16_bf16 v[16:31], v[8:11], v[108:111], v[16:31]
	ds_read_b128 v[8:11], v3 offset:18464
	s_waitcnt lgkmcnt(7)
	v_mfma_f32_32x32x16_bf16 v[16:31], v[12:15], v[96:99], v[16:31]
	ds_read_b128 v[12:15], v3 offset:18496
	s_waitcnt lgkmcnt(7)
	v_mfma_f32_32x32x16_bf16 v[16:31], v[112:115], v[104:107], v[16:31]
	ds_read_b128 v[112:115], v3 offset:18528
	s_waitcnt lgkmcnt(7)
	v_mfma_f32_32x32x16_bf16 v[64:79], v[116:119], v[100:103], v[64:79]
	ds_read_b128 v[116:119], v3 offset:23040
	s_waitcnt lgkmcnt(7)
	v_mfma_f32_32x32x16_bf16 v[64:79], v[120:123], v[108:111], v[64:79]
	ds_read_b128 v[120:123], v3 offset:23072
	s_waitcnt lgkmcnt(7)
	v_mfma_f32_32x32x16_bf16 v[64:79], v[124:127], v[96:99], v[64:79]
	ds_read_b128 v[124:127], v3 offset:23104
	s_waitcnt lgkmcnt(7)
	v_mfma_f32_32x32x16_bf16 v[64:79], v[172:175], v[104:107], v[64:79]
	ds_read_b128 v[172:175], v3 offset:23136
	s_waitcnt lgkmcnt(7)
	v_mfma_f32_32x32x16_bf16 v[48:63], v[168:171], v[100:103], v[48:63]
	s_waitcnt lgkmcnt(6)
	v_mfma_f32_32x32x16_bf16 v[48:63], v[8:11], v[108:111], v[48:63]
	s_waitcnt lgkmcnt(5)
	v_mfma_f32_32x32x16_bf16 v[48:63], v[12:15], v[96:99], v[48:63]
	s_waitcnt lgkmcnt(4)
	v_mfma_f32_32x32x16_bf16 v[48:63], v[112:115], v[104:107], v[48:63]
	s_waitcnt lgkmcnt(3)
	v_mfma_f32_32x32x16_bf16 v[32:47], v[116:119], v[100:103], v[32:47]
	s_waitcnt lgkmcnt(2)
	v_mfma_f32_32x32x16_bf16 v[32:47], v[120:123], v[108:111], v[32:47]
	s_waitcnt lgkmcnt(1)
	v_mfma_f32_32x32x16_bf16 v[32:47], v[124:127], v[96:99], v[32:47]
	s_waitcnt lgkmcnt(0)
	v_mfma_f32_32x32x16_bf16 v[32:47], v[172:175], v[104:107], v[32:47]

.LBB0_1355:
	s_and_b64 vcc, exec, s[4:5]
	s_cbranch_vccnz .Lpb_early_done
	s_mul_i32 s12, s19, 0x6c00
	v_add_u32_e32 v209, s12, v236
	ds_read_b128 v[216:219], v209 offset:9216
	ds_read_b128 v[180:183], v209 offset:9248
	ds_read_b128 v[184:187], v209 offset:9280
	ds_read_b128 v[188:191], v209 offset:9312
	ds_read_b128 v[238:241], v209 offset:13824
	ds_read_b128 v[242:245], v209 offset:13856
	ds_read_b128 v[246:249], v209 offset:13888
	ds_read_b128 v[250:253], v209 offset:13920

.LBB0_1357:
	s_setprio 1
	s_and_b64 vcc, exec, s[4:5]
	s_cbranch_vccnz .LBB0_1359
	s_mul_i32 s12, s19, 0x6c00
	v_add_u32_e32 v208, s12, v236
	s_waitcnt lgkmcnt(7)
	v_mfma_f32_32x32x16_bf16 v[80:95], v[216:219], v[164:167], v[80:95]
	ds_read_b128 v[216:219], v208 offset:18432
	s_waitcnt lgkmcnt(7)
	v_mfma_f32_32x32x16_bf16 v[80:95], v[180:183], v[172:175], v[80:95]
	ds_read_b128 v[180:183], v208 offset:18464
	s_waitcnt lgkmcnt(7)
	v_mfma_f32_32x32x16_bf16 v[80:95], v[184:187], v[160:163], v[80:95]
	ds_read_b128 v[184:187], v208 offset:18496
	s_waitcnt lgkmcnt(7)
	v_mfma_f32_32x32x16_bf16 v[80:95], v[188:191], v[168:171], v[80:95]
	ds_read_b128 v[188:191], v208 offset:18528
	s_waitcnt lgkmcnt(7)
	v_mfma_f32_32x32x16_bf16 v[128:143], v[238:241], v[164:167], v[128:143]
	ds_read_b128 v[238:241], v208 offset:23040
	s_waitcnt lgkmcnt(7)
	v_mfma_f32_32x32x16_bf16 v[128:143], v[242:245], v[172:175], v[128:143]
	ds_read_b128 v[242:245], v208 offset:23072
	s_waitcnt lgkmcnt(7)
	v_mfma_f32_32x32x16_bf16 v[128:143], v[246:249], v[160:163], v[128:143]
	ds_read_b128 v[246:249], v208 offset:23104
	s_waitcnt lgkmcnt(7)
	v_mfma_f32_32x32x16_bf16 v[128:143], v[250:253], v[168:171], v[128:143]
	ds_read_b128 v[250:253], v208 offset:23136
	s_waitcnt lgkmcnt(7)
	v_mfma_f32_32x32x16_bf16 v[112:127], v[216:219], v[164:167], v[112:127]
	s_waitcnt lgkmcnt(6)
	v_mfma_f32_32x32x16_bf16 v[112:127], v[180:183], v[172:175], v[112:127]
	s_waitcnt lgkmcnt(5)
	v_mfma_f32_32x32x16_bf16 v[112:127], v[184:187], v[160:163], v[112:127]
	s_waitcnt lgkmcnt(4)
	v_mfma_f32_32x32x16_bf16 v[112:127], v[188:191], v[168:171], v[112:127]
	s_waitcnt lgkmcnt(3)
	v_mfma_f32_32x32x16_bf16 v[96:111], v[238:241], v[164:167], v[96:111]
	s_waitcnt lgkmcnt(2)
	v_mfma_f32_32x32x16_bf16 v[96:111], v[242:245], v[172:175], v[96:111]
	s_waitcnt lgkmcnt(1)
	v_mfma_f32_32x32x16_bf16 v[96:111], v[246:249], v[160:163], v[96:111]
	s_waitcnt lgkmcnt(0)
	v_mfma_f32_32x32x16_bf16 v[96:111], v[250:253], v[168:171], v[96:111]
